# gemm_out: 256x256 tiles for 16 panels per XCD group (2 even rounds), the 17th panel of the first layer through the original 256x128 loop
# baseline (speedup 1.0000x reference)
.Lgo_235:
	s_and_b32 s1, 0xffff, s1
	s_and_b64 s[6:7], s[90:91], exec
	s_movk_i32 s6, 0x80
	s_cselect_b32 s6, s6, 0x88
	s_lshr_b32 s1, s6, s1
	s_min_u32 s6, s1, 16
	s_lshl_b32 s6, s6, 2
	s_cmp_ge_i32 s4, s6
	s_cbranch_scc1 .Lgo_end
	v_ashrrev_i32_e32 v1, 6, v0
	v_lshrrev_b32_e32 v3, 30, v1
	v_add_u32_e32 v3, v1, v3
	s_mul_i32 s7, s0, s1
	s_lshl_b32 s0, s74, 21
	s_add_u32 s0, s0, 0xc40000
	v_ashrrev_i32_e32 v3, 2, v3
	s_add_u32 s0, s50, s0
	s_waitcnt vmcnt(6)
	v_and_b32_e32 v4, 7, v0
	v_mul_i32_i24_e32 v8, 4, v3
	s_addc_u32 s1, s51, 0
	v_and_b32_e32 v2, 31, v0
	v_lshlrev_b32_e32 v128, 4, v4
	v_sub_u32_e32 v9, v1, v8
	v_lshlrev_b32_e32 v153, 7, v3
	v_ashrrev_i32_e32 v152, 3, v0
	v_bfe_u32 v6, v0, 5, 1
	v_readlane_b32 s8, v253, 38
	v_lshl_add_u64 v[176:177], s[0:1], 0, v[128:129]
	s_movk_i32 s0, 0x90
	v_or_b32_e32 v3, v153, v2
	v_lshl_or_b32 v9, v9, 6, v2
	v_readlane_b32 s9, v253, 39
	v_mul_lo_u32 v7, v152, s0
	v_mul_lo_u32 v3, v3, s0
	v_lshlrev_b32_e32 v10, 4, v6
	v_mul_lo_u32 v9, v9, s0
	v_readlane_b32 s0, v255, 15
	v_readlane_b32 s1, v255, 16
	v_lshl_add_u64 v[250:251], s[8:9], 0, v[128:129]
	v_add3_u32 v154, 0, v3, v10
	v_add_u32_e32 v13, s1, v7
	v_readlane_b32 s8, v255, 17
	v_add3_u32 v155, s0, v3, v10
	v_add_u32_e32 v3, s1, v9
	s_movk_i32 s1, 0x1200
	v_add_u32_e32 v14, s8, v7
	v_readlane_b32 s8, v255, 18
	v_mul_lo_u32 v1, v1, s1
	v_lshlrev_b32_e32 v5, 3, v4
	v_add_u32_e32 v12, s0, v7
	v_add_u32_e32 v15, s8, v7
	v_readlane_b32 s8, v255, 19
	v_add_u32_e32 v1, s0, v1
	v_lshlrev_b32_e32 v2, 1, v2
	v_mul_u32_u24_e32 v6, 0x240, v6
	v_bfe_u32 v157, v0, 3, 3
	s_movk_i32 s0, 0xffc0
	v_add_u32_e32 v4, 0, v128
	v_add_u32_e32 v11, 0, v9
	s_waitcnt vmcnt(3)
	v_add_u32_e32 v16, s8, v7
	v_add_u32_e32 v9, 0, v7
	v_add_u32_e32 v17, v1, v128
	v_add3_u32 v156, v1, v2, v6
	v_mul_u32_u24_e32 v1, 0x90, v157
	v_and_or_b32 v0, v0, s0, v5
	v_lshlrev_b32_e32 v2, 6, v8
	v_mov_b32_e32 v180, 0x2000
	v_or_b32_e32 v171, 8, v157
	v_or_b32_e32 v252, 16, v157
	v_or_b32_e32 v181, 24, v157
	v_sub_u32_e32 v179, v0, v2
	s_lshl_b32 s8, s4, 8
	s_lshl_b32 s9, s5, 8
	v_add_u32_e32 v162, v4, v7
	v_add_u32_e32 v163, v11, v10
	v_add_u32_e32 v164, v12, v128
	v_add_u32_e32 v165, v13, v128
	v_add_u32_e32 v166, v14, v128
	v_add_u32_e32 v167, v15, v128
	v_add_u32_e32 v168, v16, v128
	v_add_u32_e32 v169, v3, v10
	v_add_u32_e32 v128, v9, v128
	v_add_u32_e32 v170, v17, v1
	s_branch .Lgo_239

.Lgo_end:
	s_mov_b64 exec, -1
	v_mov_b32_e32 v0, v143
	s_and_b64 vcc, exec, s[72:73]
	s_cbranch_vccz .LBB0_1183
	v_readlane_b32 s6, v255, 23
	s_mov_b32 s1, 0
	s_mov_b32 s0, 0
	v_readlane_b32 s4, v253, 0
	v_readlane_b32 s7, v255, 24
	s_mov_b32 s5, s6
	s_branch .LBB0_1184

.LBB0_1184:
	s_add_i32 s4, s4, 0x80
	s_and_b64 s[6:7], s[90:91], exec
	s_movk_i32 s6, 0x80
	s_cselect_b32 s6, s6, 0x88
	s_and_b32 s1, 0xffff, s1
	s_lshr_b32 s1, s6, s1
	s_lshl_b32 s6, s1, 3
	s_cmp_ge_i32 s4, s6
	s_mov_b32 s13, 0x20000
	s_cbranch_scc1 .LBB0_1191
	v_ashrrev_i32_e32 v1, 6, v0
	v_lshrrev_b32_e32 v3, 31, v0
	s_mul_i32 s7, s0, s1
	s_lshl_b32 s0, s74, 21
	v_readlane_b32 s1, v253, 56
	v_add_u32_e32 v3, v1, v3
	s_add_u32 s0, s1, s0
	v_readlane_b32 s1, v253, 57
	v_ashrrev_i32_e32 v4, 1, v3
	v_and_b32_e32 v5, 7, v0
	v_and_b32_e32 v3, 0x3ffffe, v3
	s_addc_u32 s1, s1, 0
	v_and_b32_e32 v2, 31, v0
	v_sub_u32_e32 v3, v1, v3
	v_lshlrev_b32_e32 v128, 4, v5
	v_lshlrev_b32_e32 v97, 6, v4
	v_ashrrev_i32_e32 v96, 3, v0
	v_bfe_u32 v7, v0, 5, 1
	v_lshl_add_u64 v[82:83], s[0:1], 0, v[128:129]
	s_movk_i32 s0, 0x90
	v_or_b32_e32 v9, v97, v2
	v_lshl_or_b32 v3, v3, 6, v2
	v_mul_lo_u32 v8, v96, s0
	v_mul_lo_u32 v9, v9, s0
	v_lshlrev_b32_e32 v10, 4, v7
	v_mul_lo_u32 v3, v3, s0
	v_readlane_b32 s0, v255, 20
	v_add3_u32 v98, 0, v9, v10
	v_add_u32_e32 v9, 0, v3
	v_add_u32_e32 v12, s0, v8
	v_add_u32_e32 v3, s0, v3
	s_movk_i32 s0, 0x1200
	v_mul_lo_u32 v1, v1, s0
	v_bfe_u32 v100, v0, 3, 3
	v_lshlrev_b32_e32 v6, 3, v5
	v_readlane_b32 s8, v253, 38
	v_add_u32_e32 v99, 0, v8
	v_readlane_b32 s1, v255, 21
	v_add_u32_e32 v1, 0, v1
	v_or_b32_e32 v101, 8, v100
	s_movk_i32 s0, 0xffc0
	v_readlane_b32 s9, v253, 39
	v_add_u32_e32 v5, 0, v128
	v_add_u32_e32 v11, 0xd800, v99
	v_add_u32_e32 v13, s1, v8
	v_lshl_add_u32 v2, v2, 1, v1
	v_add_u32_e32 v1, v1, v128
	v_mul_u32_u24_e32 v14, 0x90, v100
	v_mul_u32_u24_e32 v7, 0x240, v7
	v_mul_u32_u24_e32 v15, 0x90, v101
	v_and_or_b32 v0, v0, s0, v6
	v_lshlrev_b32_e32 v4, 7, v4
	v_mov_b32_e32 v64, 0
	v_lshl_add_u64 v[80:81], s[8:9], 0, v[128:129]
	v_or_b32_e32 v102, 16, v100
	v_or_b32_e32 v103, 24, v100
	v_sub_u32_e32 v104, v0, v4
	s_lshl_b32 s8, s4, 7
	s_lshl_b32 s9, s5, 7
	s_mov_b64 s[0:1], 0
	v_add_u32_e32 v105, v5, v8
	v_add_u32_e32 v106, v9, v10
	v_add_u32_e32 v107, v11, v128
	v_add_u32_e32 v108, v12, v128
	v_add_u32_e32 v109, v13, v128
	v_add_u32_e32 v110, v3, v10
	v_add_u32_e32 v111, v2, v7
	v_add_u32_e32 v112, v1, v14
	v_add_u32_e32 v113, v1, v15
	v_mov_b32_e32 v65, v64
	v_mov_b32_e32 v66, v64
	v_mov_b32_e32 v67, v64
	v_mov_b32_e32 v68, v64
	v_mov_b32_e32 v69, v64
	v_mov_b32_e32 v70, v64
	v_mov_b32_e32 v71, v64
	v_mov_b32_e32 v72, v64
	v_mov_b32_e32 v73, v64
	v_mov_b32_e32 v74, v64
	v_mov_b32_e32 v75, v64
	v_mov_b32_e32 v76, v64
	v_mov_b32_e32 v77, v64
	v_mov_b32_e32 v78, v64
	v_mov_b32_e32 v79, v64
	s_branch .LBB0_1187
